# softmax VALU spread over the MFMA gaps by issue cost (v_exp counted 2) instead of by instruction count
# speedup vs baseline: 1.0053x; 1.0053x over previous
; #define LAS __attribute__((address_space(3)))
; __device__ __forceinline__ void softmax_blk(f32x16& p0, f32x16& p1, f32x16& o0, f32x16& o1, float& mhat, float& lrun, u32x4 (&pf)[4], bool first) {
;     float r0 = max2_(p0[0], p0[1]), r1 = max2_(p1[0], p1[1]);
; #pragma unroll
;     for (int e = 2; e < 16; ++e) { r0 = max2_(r0, p0[e]); r1 = max2_(r1, p1[e]); }
;     const float rm = swap_max(max2_(r0, r1));
;     if (first || __any(rm - mhat > THR)) {
;         const float mn = first ? rm : fmaxf(rm, mhat); const float f = first ? 0.f : __builtin_amdgcn_exp2f(mhat - mn); mhat = mn; lrun *= f;
; #pragma unroll
;         for (int e = 0; e < 16; ++e) { o0[e] *= f; o1[e] *= f; }
;     }
;     float s0 = 0.f, s1 = 0.f;
; #pragma unroll
;     for (int e = 0; e < 16; ++e) { p0[e] = __builtin_amdgcn_exp2f(p0[e] - mhat); p1[e] = __builtin_amdgcn_exp2f(p1[e] - mhat); s0 += p0[e]; s1 += p1[e]; }
;     lrun += s0 + s1;
;     pf[0] = MLA_PACK(p0, 0); pf[1] = MLA_PACK(p0, 8); pf[2] = MLA_PACK(p1, 0); pf[3] = MLA_PACK(p1, 8);
; }
; __device__ __forceinline__ void attn_unit(const bf16_t* Qh, const bf16_t* Kh, const bf16_t* Vh, bf16_t* Oh  , int S, int qb, LAS unsigned char* lds, int tid) {
;     ...
;         {
;             f32x16 p0 = {}, p1 = {};
; #pragma unroll
;             for (int s = 0; s < 6; ++s) {
;                 const bf16x8 a0 = *(const LAS bf16x8*)(lds + cur + kfo + s * 32), a1 = *(const LAS bf16x8*)(lds + cur + kfo + 32 * KPITCH + s * 32);
;                 const bf16x8 q = *(const LAS bf16x8*)(ql + s * 1024);
;                 p0 = __builtin_amdgcn_mfma_f32_32x32x16_bf16(a0, q, p0, 0, 0, 0); p1 = __builtin_amdgcn_mfma_f32_32x32x16_bf16(a1, q, p1, 0, 0, 0);
;             }
;             softmax_blk(p0, p1, oa0, oa1, ma, la, pf, t == 0);
;             pv_blk(pf, oa0, oa1, lds + cur + vb);
;         }
;         __builtin_amdgcn_sched_barrier(0);
;         {
;             f32x16 p0 = {}, p1 = {};
; #pragma unroll
;             for (int s = 0; s < 6; ++s) {
;                 const bf16x8 a0 = *(const LAS bf16x8*)(lds + cur + kfo + s * 32), a1 = *(const LAS bf16x8*)(lds + cur + kfo + 32 * KPITCH + s * 32);
;                 const bf16x8 q = *(const LAS bf16x8*)(ql + (6 + s) * 1024);
;                 p0 = __builtin_amdgcn_mfma_f32_32x32x16_bf16(a0, q, p0, 0, 0, 0); p1 = __builtin_amdgcn_mfma_f32_32x32x16_bf16(a1, q, p1, 0, 0, 0);
;             }
.Lmla_prio:
	s_add_u32 s100, s100, 0x2000
	s_addc_u32 s101, s101, 0
	ds_read_b128 v[128:131], v155
	ds_read_b128 v[142:145], v155 offset:6656
	ds_read_b128 v[162:165], v135 offset:43008
	ds_read_b128 v[176:179], v155 offset:32
	ds_read_b128 v[180:183], v155 offset:6688
	ds_read_b128 v[186:189], v135 offset:44032
	s_waitcnt lgkmcnt(3)
	v_mfma_f32_32x32x16_bf16 v[64:79], v[128:131], v[162:165], 0
	v_mfma_f32_32x32x16_bf16 v[80:95], v[142:145], v[162:165], 0
	ds_read_b128 v[128:131], v155 offset:64
	ds_read_b128 v[142:145], v155 offset:6720
	ds_read_b128 v[162:165], v135 offset:45056
	global_load_dwordx4 v[218:221], v171, s[26:27]
	global_load_dwordx4 v[222:225], v184, s[26:27]
	s_add_u32 s26, s26, 0x3000
	s_addc_u32 s27, s27, 0
	s_waitcnt lgkmcnt(3)
	v_mfma_f32_32x32x16_bf16 v[64:79], v[176:179], v[186:189], v[64:79]
	v_mfma_f32_32x32x16_bf16 v[80:95], v[180:183], v[186:189], v[80:95]
	ds_read_b128 v[176:179], v155 offset:96
	ds_read_b128 v[180:183], v155 offset:6752
	ds_read_b128 v[186:189], v135 offset:46080
	s_waitcnt lgkmcnt(3)
	v_mfma_f32_32x32x16_bf16 v[64:79], v[128:131], v[162:165], v[64:79]
	v_mfma_f32_32x32x16_bf16 v[80:95], v[142:145], v[162:165], v[80:95]
	ds_read_b128 v[128:131], v155 offset:128
	ds_read_b128 v[142:145], v155 offset:6784
	ds_read_b128 v[162:165], v135 offset:47104
	s_waitcnt lgkmcnt(3)
	v_mfma_f32_32x32x16_bf16 v[64:79], v[176:179], v[186:189], v[64:79]
	v_mfma_f32_32x32x16_bf16 v[80:95], v[180:183], v[186:189], v[80:95]
	ds_read_b128 v[176:179], v155 offset:160
	ds_read_b128 v[180:183], v155 offset:6816
	ds_read_b128 v[186:189], v135 offset:48128
	s_waitcnt lgkmcnt(3)
	v_mfma_f32_32x32x16_bf16 v[64:79], v[128:131], v[162:165], v[64:79]
	v_mfma_f32_32x32x16_bf16 v[80:95], v[142:145], v[162:165], v[80:95]
	ds_read_b128 v[128:131], v155
	ds_read_b128 v[142:145], v155 offset:6656
	ds_read_b128 v[162:165], v135 offset:49152
	s_waitcnt lgkmcnt(3)
	v_mfma_f32_32x32x16_bf16 v[64:79], v[176:179], v[186:189], v[64:79]
	v_mfma_f32_32x32x16_bf16 v[80:95], v[180:183], v[186:189], v[80:95]
	ds_read_b128 v[176:179], v155 offset:32
	ds_read_b128 v[180:183], v155 offset:6688
	ds_read_b128 v[186:189], v135 offset:50176
	s_waitcnt lgkmcnt(3)
	v_mfma_f32_32x32x16_bf16 v[96:111], v[128:131], v[162:165], 0
	v_mfma_f32_32x32x16_bf16 v[112:127], v[142:145], v[162:165], 0
	ds_read_b128 v[128:131], v155 offset:64
	ds_read_b128 v[142:145], v155 offset:6720
	ds_read_b128 v[162:165], v135 offset:51200
	s_nop 5
	v_max3_f32 v248, v64, v65, v66
	v_max3_f32 v249, v80, v81, v82
	v_max3_f32 v248, v248, v67, v68
	v_max3_f32 v249, v249, v83, v84
	v_max3_f32 v248, v248, v69, v70
	v_max3_f32 v249, v249, v85, v86
	v_max3_f32 v248, v248, v71, v72
	v_max3_f32 v249, v249, v87, v88
	v_max3_f32 v248, v248, v73, v74
	v_max3_f32 v249, v249, v89, v90
	v_max3_f32 v248, v248, v75, v76
	v_max3_f32 v249, v249, v91, v92
	v_max3_f32 v248, v248, v77, v78
	v_max3_f32 v249, v249, v93, v94
	v_max3_f32 v248, v248, v79, v95
	v_max_f32_e32 v248, v248, v249
	v_mov_b32_e32 v251, v248
	s_nop 1
	v_permlane32_swap_b32_e32 v248, v251
	v_max_f32_e32 v167, v248, v251
	v_sub_f32_e32 v64, v64, v167
	v_sub_f32_e32 v65, v65, v167
	v_sub_f32_e32 v66, v66, v167
	v_sub_f32_e32 v67, v67, v167
	v_sub_f32_e32 v68, v68, v167
	v_sub_f32_e32 v69, v69, v167
	v_sub_f32_e32 v70, v70, v167
	v_sub_f32_e32 v71, v71, v167
	v_sub_f32_e32 v72, v72, v167
	v_sub_f32_e32 v73, v73, v167
	v_sub_f32_e32 v74, v74, v167
	v_sub_f32_e32 v75, v75, v167
	v_sub_f32_e32 v76, v76, v167
	v_sub_f32_e32 v77, v77, v167
	s_waitcnt lgkmcnt(3)
	v_mfma_f32_32x32x16_bf16 v[96:111], v[176:179], v[186:189], v[96:111]
	v_mfma_f32_32x32x16_bf16 v[112:127], v[180:183], v[186:189], v[112:127]
	ds_read_b128 v[176:179], v155 offset:96
	ds_read_b128 v[180:183], v155 offset:6752
	ds_read_b128 v[186:189], v135 offset:52224
	v_sub_f32_e32 v78, v78, v167
	v_sub_f32_e32 v79, v79, v167
	v_sub_f32_e32 v80, v80, v167
	v_sub_f32_e32 v81, v81, v167
	v_sub_f32_e32 v82, v82, v167
	v_sub_f32_e32 v83, v83, v167
	v_sub_f32_e32 v84, v84, v167
	v_sub_f32_e32 v85, v85, v167
	v_sub_f32_e32 v86, v86, v167
	v_sub_f32_e32 v87, v87, v167
	v_sub_f32_e32 v88, v88, v167
	v_sub_f32_e32 v89, v89, v167
	v_sub_f32_e32 v90, v90, v167
	v_sub_f32_e32 v91, v91, v167
	v_sub_f32_e32 v92, v92, v167
	v_sub_f32_e32 v93, v93, v167
	v_sub_f32_e32 v94, v94, v167
	v_sub_f32_e32 v95, v95, v167
	v_sub_f32_e32 v232, 0, v167
	v_sub_f32_e32 v233, 0, v167
	v_sub_f32_e32 v234, 0, v167
	v_sub_f32_e32 v235, 0, v167
	v_sub_f32_e32 v236, 0, v167
	v_sub_f32_e32 v237, 0, v167
	v_sub_f32_e32 v238, 0, v167
	v_sub_f32_e32 v239, 0, v167
	v_sub_f32_e32 v240, 0, v167
	v_sub_f32_e32 v241, 0, v167
	v_sub_f32_e32 v242, 0, v167
	v_sub_f32_e32 v243, 0, v167
	v_sub_f32_e32 v244, 0, v167
	v_sub_f32_e32 v245, 0, v167
	v_sub_f32_e32 v246, 0, v167
	v_sub_f32_e32 v247, 0, v167
	s_waitcnt lgkmcnt(3)
	v_mfma_f32_32x32x16_bf16 v[96:111], v[128:131], v[162:165], v[96:111]
	v_mfma_f32_32x32x16_bf16 v[112:127], v[142:145], v[162:165], v[112:127]
	ds_read_b128 v[128:131], v155 offset:128
	ds_read_b128 v[142:145], v155 offset:6784
	ds_read_b128 v[162:165], v135 offset:53248
	v_max3_f32 v248, v64, v65, v66
	v_max3_f32 v249, v80, v81, v82
	v_max3_f32 v248, v248, v67, v68
	v_max3_f32 v249, v249, v83, v84
	v_max3_f32 v248, v248, v69, v70
	v_max3_f32 v249, v249, v85, v86
	v_max3_f32 v248, v248, v71, v72
	v_max3_f32 v249, v249, v87, v88
	v_max3_f32 v248, v248, v73, v74
	v_max3_f32 v249, v249, v89, v90
	v_max3_f32 v248, v248, v75, v76
	v_max3_f32 v249, v249, v91, v92
	v_max3_f32 v248, v248, v77, v78
	v_max3_f32 v249, v249, v93, v94
	v_max3_f32 v248, v248, v79, v95
	v_max_f32_e32 v248, v248, v249
	v_mov_b32_e32 v251, v248
	s_nop 1
	v_permlane32_swap_b32_e32 v248, v251
	v_max_f32_e32 v167, v248, v251
	v_cmp_lt_f32_e32 vcc, s72, v167
	s_cbranch_vccnz .Lmla_rescAp
; #define LAS __attribute__((address_space(3)))
; __device__ __forceinline__ float swap_max(float m) { auto rr = __builtin_amdgcn_permlane32_swap(__float_as_uint(m), __float_as_uint(m), false, false); return fmaxf(__uint_as_float(rr[0]), __uint_as_float(rr[1])); }
; #define MLA_PACK(P, b) (u32x4){cvt_pk_bf16(P[b], P[b + 1]), cvt_pk_bf16(P[b + 2], P[b + 3]), cvt_pk_bf16(P[b + 4], P[b + 5]), cvt_pk_bf16(P[b + 6], P[b + 7])}
; __device__ __forceinline__ void softmax_blk(f32x16& p0, f32x16& p1, f32x16& o0, f32x16& o1, float& mhat, float& lrun, u32x4 (&pf)[4], bool first) {
;     float r0 = max2_(p0[0], p0[1]), r1 = max2_(p1[0], p1[1]);
; #pragma unroll
;     for (int e = 2; e < 16; ++e) { r0 = max2_(r0, p0[e]); r1 = max2_(r1, p1[e]); }
;     const float rm = swap_max(max2_(r0, r1));
;     if (first || __any(rm - mhat > THR)) {
;         const float mn = first ? rm : fmaxf(rm, mhat); const float f = first ? 0.f : __builtin_amdgcn_exp2f(mhat - mn); mhat = mn; lrun *= f;
; #pragma unroll
;         for (int e = 0; e < 16; ++e) { o0[e] *= f; o1[e] *= f; }
;     }
;     float s0 = 0.f, s1 = 0.f;
; #pragma unroll
;     for (int e = 0; e < 16; ++e) { p0[e] = __builtin_amdgcn_exp2f(p0[e] - mhat); p1[e] = __builtin_amdgcn_exp2f(p1[e] - mhat); s0 += p0[e]; s1 += p1[e]; }
;     lrun += s0 + s1;
;     pf[0] = MLA_PACK(p0, 0); pf[1] = MLA_PACK(p0, 8); pf[2] = MLA_PACK(p1, 0); pf[3] = MLA_PACK(p1, 8);
; }
; __device__ __forceinline__ void attn_unit(const bf16_t* Qh, const bf16_t* Kh, const bf16_t* Vh, bf16_t* Oh  , int S, int qb, LAS unsigned char* lds, int tid) {
;     ...
;         {
;             f32x16 p0 = {}, p1 = {};
; #pragma unroll
;             for (int s = 0; s < 6; ++s) {
;                 const bf16x8 a0 = *(const LAS bf16x8*)(lds + cur + kfo + s * 32), a1 = *(const LAS bf16x8*)(lds + cur + kfo + 32 * KPITCH + s * 32);
;                 const bf16x8 q = *(const LAS bf16x8*)(ql + (6 + s) * 1024);
;                 p0 = __builtin_amdgcn_mfma_f32_32x32x16_bf16(a0, q, p0, 0, 0, 0); p1 = __builtin_amdgcn_mfma_f32_32x32x16_bf16(a1, q, p1, 0, 0, 0);
;             }
;             softmax_blk(p0, p1, ob0, ob1, mb, lb, pf, t == 0);
;             pv_blk(pf, ob0, ob1, lds + cur + vb);
;         }
;         *(LAS u32x4*)(lds + nxt + kd0) = ka; *(LAS u32x4*)(lds + (has1 ? nxt : 0u) + kd1) = kb; *(LAS u32x4*)(lds + nxt + vd) = va;
;         __syncthreads();
.Lmla_rescAp_back:
	v_exp_f32_e32 v64, v64
	v_exp_f32_e32 v65, v65
	v_exp_f32_e32 v66, v66
	v_exp_f32_e32 v67, v67
	v_exp_f32_e32 v68, v68
	v_exp_f32_e32 v69, v69
	s_waitcnt lgkmcnt(3)
	v_mfma_f32_32x32x16_bf16 v[96:111], v[176:179], v[186:189], v[96:111]
	v_mfma_f32_32x32x16_bf16 v[112:127], v[180:183], v[186:189], v[112:127]
	ds_read_b128 v[176:179], v155 offset:160
	ds_read_b128 v[180:183], v155 offset:6816
	ds_read_b128 v[186:189], v135 offset:54272
	v_exp_f32_e32 v70, v70
	v_exp_f32_e32 v71, v71
	v_add_f32_e32 v166, v64, v65
	v_add_f32_e32 v140, v140, v66
	v_add_f32_e32 v166, v166, v67
	v_cvt_pk_bf16_f32 v64, v64, v65
	v_cvt_pk_bf16_f32 v65, v66, v67
	v_exp_f32_e32 v72, v72
	v_exp_f32_e32 v73, v73
	v_exp_f32_e32 v74, v74
	v_exp_f32_e32 v75, v75
	v_add_f32_e32 v140, v140, v68
	v_add_f32_e32 v166, v166, v69
	v_add_f32_e32 v140, v140, v70
	v_add_f32_e32 v166, v166, v71
	v_cvt_pk_bf16_f32 v66, v68, v69
	v_cvt_pk_bf16_f32 v67, v70, v71
	v_exp_f32_e32 v76, v76
	v_exp_f32_e32 v77, v77
	v_exp_f32_e32 v78, v78
	v_exp_f32_e32 v79, v79
	v_add_f32_e32 v140, v140, v72
	v_add_f32_e32 v166, v166, v73
	s_waitcnt lgkmcnt(3)
	v_mfma_f32_32x32x16_bf16 v[96:111], v[128:131], v[162:165], v[96:111]
	v_mfma_f32_32x32x16_bf16 v[112:127], v[142:145], v[162:165], v[112:127]
	v_add_f32_e32 v140, v140, v74
	v_add_f32_e32 v166, v166, v75
	v_cvt_pk_bf16_f32 v68, v72, v73
	v_cvt_pk_bf16_f32 v69, v74, v75
	v_exp_f32_e32 v80, v80
	v_exp_f32_e32 v81, v81
	v_exp_f32_e32 v82, v82
	v_exp_f32_e32 v83, v83
	v_add_f32_e32 v140, v140, v76
	v_add_f32_e32 v166, v166, v77
	v_add_f32_e32 v140, v140, v78
	v_add_f32_e32 v166, v166, v79
	v_cvt_pk_bf16_f32 v70, v76, v77
	v_cvt_pk_bf16_f32 v71, v78, v79
	v_exp_f32_e32 v84, v84
	v_exp_f32_e32 v85, v85
	v_exp_f32_e32 v86, v86
	v_exp_f32_e32 v87, v87
	v_add_f32_e32 v140, v140, v80
	v_add_f32_e32 v166, v166, v81
	v_add_f32_e32 v140, v140, v82
	v_add_f32_e32 v166, v166, v83
	v_cvt_pk_bf16_f32 v72, v80, v81
	v_cvt_pk_bf16_f32 v73, v82, v83
	v_exp_f32_e32 v88, v88
	s_waitcnt lgkmcnt(0)
	v_mfma_f32_32x32x16_bf16 v[96:111], v[176:179], v[186:189], v[96:111]
	v_mfma_f32_32x32x16_bf16 v[112:127], v[180:183], v[186:189], v[112:127]
	v_exp_f32_e32 v89, v89
	v_exp_f32_e32 v90, v90
	v_exp_f32_e32 v91, v91
	v_add_f32_e32 v140, v140, v84
	v_add_f32_e32 v166, v166, v85
	v_add_f32_e32 v140, v140, v86
	v_add_f32_e32 v166, v166, v87
	v_cvt_pk_bf16_f32 v74, v84, v85
	v_cvt_pk_bf16_f32 v75, v86, v87
	v_exp_f32_e32 v92, v92
	v_exp_f32_e32 v93, v93
	v_exp_f32_e32 v94, v94
	v_exp_f32_e32 v95, v95
	v_add_f32_e32 v140, v140, v88
	v_add_f32_e32 v166, v166, v89
	v_add_f32_e32 v140, v140, v90
	v_add_f32_e32 v166, v166, v91
	v_cvt_pk_bf16_f32 v76, v88, v89
	v_cvt_pk_bf16_f32 v77, v90, v91
	v_add_f32_e32 v140, v140, v92
	v_add_f32_e32 v166, v166, v93
	v_add_f32_e32 v140, v140, v94
	v_add_f32_e32 v166, v166, v95
	v_cvt_pk_bf16_f32 v78, v92, v93
	v_cvt_pk_bf16_f32 v79, v94, v95
	v_add_f32_e32 v140, v140, v166
	s_nop 7
	s_nop 3
	v_max3_f32 v248, v96, v97, v98
	v_max3_f32 v249, v112, v113, v114
	v_max3_f32 v248, v248, v99, v100
	v_max3_f32 v249, v249, v115, v116
	v_max3_f32 v248, v248, v101, v102
	v_max3_f32 v249, v249, v117, v118
	v_max3_f32 v248, v248, v103, v104
	v_max3_f32 v249, v249, v119, v120
	v_max3_f32 v248, v248, v105, v106
	v_max3_f32 v249, v249, v121, v122
	v_max3_f32 v248, v248, v107, v108
	v_max3_f32 v249, v249, v123, v124
	v_max3_f32 v248, v248, v109, v110
	v_max3_f32 v249, v249, v125, v126
	v_max3_f32 v248, v248, v111, v127
	v_max_f32_e32 v248, v248, v249
	v_mov_b32_e32 v251, v248
	s_nop 1
	v_permlane32_swap_b32_e32 v248, v251
	v_max_f32_e32 v167, v248, v251
	v_sub_f32_e32 v96, v96, v167
	v_sub_f32_e32 v97, v97, v167
	v_sub_f32_e32 v98, v98, v167
	v_sub_f32_e32 v99, v99, v167
	v_sub_f32_e32 v100, v100, v167
	v_sub_f32_e32 v101, v101, v167
	v_sub_f32_e32 v102, v102, v167
	v_sub_f32_e32 v103, v103, v167
	v_sub_f32_e32 v104, v104, v167
	v_sub_f32_e32 v105, v105, v167
	v_sub_f32_e32 v106, v106, v167
	v_sub_f32_e32 v107, v107, v167
	v_sub_f32_e32 v108, v108, v167
	v_sub_f32_e32 v109, v109, v167
	v_sub_f32_e32 v110, v110, v167
	v_sub_f32_e32 v111, v111, v167
	v_sub_f32_e32 v112, v112, v167
	v_sub_f32_e32 v113, v113, v167
	v_sub_f32_e32 v114, v114, v167
	v_sub_f32_e32 v115, v115, v167
	v_sub_f32_e32 v116, v116, v167
	v_sub_f32_e32 v117, v117, v167
	v_sub_f32_e32 v118, v118, v167
	v_sub_f32_e32 v119, v119, v167
	v_sub_f32_e32 v120, v120, v167
	v_sub_f32_e32 v121, v121, v167
	v_sub_f32_e32 v122, v122, v167
	v_sub_f32_e32 v123, v123, v167
	v_sub_f32_e32 v124, v124, v167
	v_sub_f32_e32 v125, v125, v167
	v_sub_f32_e32 v126, v126, v167
	v_sub_f32_e32 v127, v127, v167
	v_sub_f32_e32 v190, 0, v167
	v_sub_f32_e32 v191, 0, v167
	v_sub_f32_e32 v192, 0, v167
	v_sub_f32_e32 v193, 0, v167
	v_sub_f32_e32 v194, 0, v167
	v_sub_f32_e32 v195, 0, v167
	v_sub_f32_e32 v196, 0, v167
	v_sub_f32_e32 v197, 0, v167
	v_sub_f32_e32 v198, 0, v167
	v_sub_f32_e32 v199, 0, v167
	v_sub_f32_e32 v200, 0, v167
	v_sub_f32_e32 v201, 0, v167
	v_sub_f32_e32 v202, 0, v167
	v_sub_f32_e32 v203, 0, v167
	v_sub_f32_e32 v204, 0, v167
	v_sub_f32_e32 v205, 0, v167
	s_waitcnt vmcnt(0)
	ds_write_b128 v150, v[218:221] offset:21504
	ds_write_b128 v159, v[222:225]
	s_waitcnt lgkmcnt(0)
	s_barrier
; #define LAS __attribute__((address_space(3)))
; __device__ __forceinline__ float max2_(float a, float b) { return __builtin_amdgcn_fmed3f(a, b, INFINITY); }
; __device__ __forceinline__ void softmax_blk(f32x16& p0, f32x16& p1, f32x16& o0, f32x16& o1, float& mhat, float& lrun, u32x4 (&pf)[4], bool first) {
;     float r0 = max2_(p0[0], p0[1]), r1 = max2_(p1[0], p1[1]);
; #pragma unroll
;     for (int e = 2; e < 16; ++e) { r0 = max2_(r0, p0[e]); r1 = max2_(r1, p1[e]); }
;     const float rm = swap_max(max2_(r0, r1));
;     if (first || __any(rm - mhat > THR)) {
;         const float mn = first ? rm : fmaxf(rm, mhat); const float f = first ? 0.f : __builtin_amdgcn_exp2f(mhat - mn); mhat = mn; lrun *= f;
; #pragma unroll
;         for (int e = 0; e < 16; ++e) { o0[e] *= f; o1[e] *= f; }
;     }
;     float s0 = 0.f, s1 = 0.f;
; #pragma unroll
;     for (int e = 0; e < 16; ++e) { p0[e] = __builtin_amdgcn_exp2f(p0[e] - mhat); p1[e] = __builtin_amdgcn_exp2f(p1[e] - mhat); s0 += p0[e]; s1 += p1[e]; }
;     lrun += s0 + s1;
;     pf[0] = MLA_PACK(p0, 0); pf[1] = MLA_PACK(p0, 8); pf[2] = MLA_PACK(p1, 0); pf[3] = MLA_PACK(p1, 8);
; }
; __device__ __forceinline__ void pv_blk(const u32x4 (&pf)[4], f32x16& o0, f32x16& o1, LAS const unsigned char* vbase) {
; #pragma unroll
;     for (int ks = 0; ks < 4; ++ks) {
;         const bf16x8 p = __builtin_bit_cast(bf16x8, pf[ks]);
;         { const s16x4 lo = vtr(vbase + ks * 1024), hh = vtr(vbase + ks * 1024 + 512); const bf16x8 vf = {lo[0], lo[1], lo[2], lo[3], hh[0], hh[1], hh[2], hh[3]};
;           o0 = __builtin_amdgcn_mfma_f32_32x32x16_bf16(vf, p, o0, 0, 0, 0); }
;         { const s16x4 lo = vtr(vbase + 4096 + ks * 1024), hh = vtr(vbase + 4096 + ks * 1024 + 512); const bf16x8 vf = {lo[0], lo[1], lo[2], lo[3], hh[0], hh[1], hh[2], hh[3]};
;           o1 = __builtin_amdgcn_mfma_f32_32x32x16_bf16(vf, p, o1, 0, 0, 0); }
;     }
; }
; __device__ __forceinline__ void attn_unit(const bf16_t* Qh, const bf16_t* Kh, const bf16_t* Vh, bf16_t* Oh  , int S, int qb, LAS unsigned char* lds, int tid) {
;     ...
;     for (int t = 0; t < NT; ++t) {
;         const unsigned cur = (unsigned)(t & 1) * BUF, nxt = BUF - cur;
;         const int tn = t + 1 < NT ? t + 1 : t;
;         ka = GLD(u32x4, Kg + (size_t)tn * 768 + kc0); kb = GLD(u32x4, Kg + (size_t)tn * 768 + kc1); va = GLD(u32x4, Vg + (size_t)tn * 512 + tid);
.Lmla_top:
	ds_read_b64_tr_b16 v[128:129], v158 offset:13312
	ds_read_b64_tr_b16 v[130:131], v158 offset:13824
	ds_read_b64_tr_b16 v[142:143], v158 offset:17408
	ds_read_b64_tr_b16 v[144:145], v158 offset:17920
	ds_read_b64_tr_b16 v[176:177], v158 offset:14336
	ds_read_b64_tr_b16 v[178:179], v158 offset:14848
	ds_read_b64_tr_b16 v[180:181], v158 offset:18432
	ds_read_b64_tr_b16 v[182:183], v158 offset:18944
	s_waitcnt lgkmcnt(4)
	v_mfma_f32_32x32x16_bf16 v[16:31], v[128:131], v[64:67], v[16:31]
	v_mfma_f32_32x32x16_bf16 v[0:15], v[142:145], v[64:67], v[0:15]
	ds_read_b64_tr_b16 v[128:129], v158 offset:15360
	ds_read_b64_tr_b16 v[130:131], v158 offset:15872
	ds_read_b64_tr_b16 v[142:143], v158 offset:19456
	ds_read_b64_tr_b16 v[144:145], v158 offset:19968
	global_load_dwordx4 v[218:221], v171, s[26:27]
	global_load_dwordx4 v[222:225], v184, s[26:27]
	global_load_dwordx4 v[226:229], v146, s[100:101]
	s_add_u32 s26, s26, 0x3000
	s_addc_u32 s27, s27, 0
	s_add_u32 s100, s100, 0x2000
	s_addc_u32 s101, s101, 0
	v_max3_f32 v248, v96, v97, v98
	v_max3_f32 v249, v112, v113, v114
	v_max3_f32 v248, v248, v99, v100
	v_max3_f32 v249, v249, v115, v116
	v_max3_f32 v248, v248, v101, v102
	v_max3_f32 v249, v249, v117, v118
	v_max3_f32 v248, v248, v103, v104
	v_max3_f32 v249, v249, v119, v120
	v_max3_f32 v248, v248, v105, v106
	v_max3_f32 v249, v249, v121, v122
	v_max3_f32 v248, v248, v107, v108
	v_max3_f32 v249, v249, v123, v124
	v_max3_f32 v248, v248, v109, v110
	v_max3_f32 v249, v249, v125, v126
	s_waitcnt lgkmcnt(4)
	v_mfma_f32_32x32x16_bf16 v[16:31], v[176:179], v[68:71], v[16:31]
	v_mfma_f32_32x32x16_bf16 v[0:15], v[180:183], v[68:71], v[0:15]
	ds_read_b64_tr_b16 v[176:177], v158 offset:16384
	ds_read_b64_tr_b16 v[178:179], v158 offset:16896
	ds_read_b64_tr_b16 v[180:181], v158 offset:20480
	ds_read_b64_tr_b16 v[182:183], v158 offset:20992
	v_max3_f32 v248, v248, v111, v127
	v_max_f32_e32 v248, v248, v249
	v_mov_b32_e32 v251, v248
	s_nop 1
	v_permlane32_swap_b32_e32 v248, v251
	v_max_f32_e32 v167, v248, v251
	v_cmp_lt_f32_e32 vcc, s72, v167
	s_cbranch_vccnz .Lmla_rescBo
.Lmla_rescBo_back:
	v_exp_f32_e32 v96, v96
	v_exp_f32_e32 v97, v97
	v_exp_f32_e32 v98, v98
	s_waitcnt lgkmcnt(4)
	v_mfma_f32_32x32x16_bf16 v[16:31], v[128:131], v[72:75], v[16:31]
	v_mfma_f32_32x32x16_bf16 v[0:15], v[142:145], v[72:75], v[0:15]
	ds_read_b128 v[128:131], v155 offset:21504
	ds_read_b128 v[142:145], v155 offset:28160
	ds_read_b128 v[162:165], v135 offset:43008
	v_exp_f32_e32 v99, v99
	v_exp_f32_e32 v100, v100
	v_exp_f32_e32 v101, v101
	v_exp_f32_e32 v102, v102
	v_exp_f32_e32 v103, v103
	v_add_f32_e32 v166, v96, v97
	v_add_f32_e32 v141, v141, v98
	v_add_f32_e32 v166, v166, v99
	s_waitcnt lgkmcnt(3)
	v_mfma_f32_32x32x16_bf16 v[16:31], v[176:179], v[76:79], v[16:31]
	v_mfma_f32_32x32x16_bf16 v[0:15], v[180:183], v[76:79], v[0:15]
	ds_read_b128 v[176:179], v155 offset:21536
	ds_read_b128 v[180:183], v155 offset:28192
	ds_read_b128 v[186:189], v135 offset:44032
	v_cvt_pk_bf16_f32 v96, v96, v97
	v_cvt_pk_bf16_f32 v97, v98, v99
	v_exp_f32_e32 v104, v104
	v_exp_f32_e32 v105, v105
	v_exp_f32_e32 v106, v106
	v_exp_f32_e32 v107, v107
	v_add_f32_e32 v141, v141, v100
	v_add_f32_e32 v166, v166, v101
	v_add_f32_e32 v141, v141, v102
	s_waitcnt lgkmcnt(3)
	v_mfma_f32_32x32x16_bf16 v[64:79], v[128:131], v[162:165], v[232:247]
	v_mfma_f32_32x32x16_bf16 v[80:95], v[142:145], v[162:165], v[232:247]
	ds_read_b128 v[128:131], v155 offset:21568
	ds_read_b128 v[142:145], v155 offset:28224
	ds_read_b128 v[162:165], v135 offset:45056
	v_add_f32_e32 v166, v166, v103
	v_cvt_pk_bf16_f32 v98, v100, v101
	v_cvt_pk_bf16_f32 v99, v102, v103
	v_exp_f32_e32 v108, v108
	v_exp_f32_e32 v109, v109
	v_exp_f32_e32 v110, v110
	v_exp_f32_e32 v111, v111
	v_add_f32_e32 v141, v141, v104
	v_add_f32_e32 v166, v166, v105
	s_waitcnt lgkmcnt(3)
	v_mfma_f32_32x32x16_bf16 v[64:79], v[176:179], v[186:189], v[64:79]
	v_mfma_f32_32x32x16_bf16 v[80:95], v[180:183], v[186:189], v[80:95]
	ds_read_b128 v[176:179], v155 offset:21600
	ds_read_b128 v[180:183], v155 offset:28256
	ds_read_b128 v[186:189], v135 offset:46080
	v_add_f32_e32 v141, v141, v106
	v_add_f32_e32 v166, v166, v107
	v_cvt_pk_bf16_f32 v100, v104, v105
	v_cvt_pk_bf16_f32 v101, v106, v107
	v_exp_f32_e32 v112, v112
	v_exp_f32_e32 v113, v113
	v_exp_f32_e32 v114, v114
	v_exp_f32_e32 v115, v115
	v_add_f32_e32 v141, v141, v108
	v_add_f32_e32 v166, v166, v109
	s_waitcnt lgkmcnt(3)
	v_mfma_f32_32x32x16_bf16 v[64:79], v[128:131], v[162:165], v[64:79]
	v_mfma_f32_32x32x16_bf16 v[80:95], v[142:145], v[162:165], v[80:95]
	ds_read_b128 v[128:131], v155 offset:21632
	ds_read_b128 v[142:145], v155 offset:28288
	ds_read_b128 v[162:165], v135 offset:47104
	v_add_f32_e32 v141, v141, v110
	v_add_f32_e32 v166, v166, v111
	v_cvt_pk_bf16_f32 v102, v108, v109
	v_cvt_pk_bf16_f32 v103, v110, v111
	v_exp_f32_e32 v116, v116
	v_exp_f32_e32 v117, v117
	v_exp_f32_e32 v118, v118
	v_exp_f32_e32 v119, v119
	v_add_f32_e32 v141, v141, v112
	s_waitcnt lgkmcnt(3)
	v_mfma_f32_32x32x16_bf16 v[64:79], v[176:179], v[186:189], v[64:79]
	v_mfma_f32_32x32x16_bf16 v[80:95], v[180:183], v[186:189], v[80:95]
	ds_read_b128 v[176:179], v155 offset:21664
	ds_read_b128 v[180:183], v155 offset:28320
	ds_read_b128 v[186:189], v135 offset:48128
	v_add_f32_e32 v166, v166, v113
	v_add_f32_e32 v141, v141, v114
	v_add_f32_e32 v166, v166, v115
	v_cvt_pk_bf16_f32 v104, v112, v113
	v_cvt_pk_bf16_f32 v105, v114, v115
	v_exp_f32_e32 v120, v120
	v_exp_f32_e32 v121, v121
	v_exp_f32_e32 v122, v122
	v_exp_f32_e32 v123, v123
	v_add_f32_e32 v141, v141, v116
	s_waitcnt lgkmcnt(3)
; __device__ __forceinline__ void softmax_blk(f32x16& p0, f32x16& p1, f32x16& o0, f32x16& o1, float& mhat, float& lrun, u32x4 (&pf)[4], bool first) {
;     float r0 = max2_(p0[0], p0[1]), r1 = max2_(p1[0], p1[1]);
; #pragma unroll
;     for (int e = 2; e < 16; ++e) { r0 = max2_(r0, p0[e]); r1 = max2_(r1, p1[e]); }
;     const float rm = swap_max(max2_(r0, r1));
;     if (first || __any(rm - mhat > THR)) {
;         const float mn = first ? rm : fmaxf(rm, mhat); const float f = first ? 0.f : __builtin_amdgcn_exp2f(mhat - mn); mhat = mn; lrun *= f;
; #pragma unroll
;         for (int e = 0; e < 16; ++e) { o0[e] *= f; o1[e] *= f; }
;     }
;     float s0 = 0.f, s1 = 0.f;
; #pragma unroll
;     for (int e = 0; e < 16; ++e) { p0[e] = __builtin_amdgcn_exp2f(p0[e] - mhat); p1[e] = __builtin_amdgcn_exp2f(p1[e] - mhat); s0 += p0[e]; s1 += p1[e]; }
;     lrun += s0 + s1;
;     pf[0] = MLA_PACK(p0, 0); pf[1] = MLA_PACK(p0, 8); pf[2] = MLA_PACK(p1, 0); pf[3] = MLA_PACK(p1, 8);
; }
; __device__ __forceinline__ void pv_blk(const u32x4 (&pf)[4], f32x16& o0, f32x16& o1, LAS const unsigned char* vbase) {
; #pragma unroll
;     for (int ks = 0; ks < 4; ++ks) {
;         const bf16x8 p = __builtin_bit_cast(bf16x8, pf[ks]);
;         { const s16x4 lo = vtr(vbase + ks * 1024), hh = vtr(vbase + ks * 1024 + 512); const bf16x8 vf = {lo[0], lo[1], lo[2], lo[3], hh[0], hh[1], hh[2], hh[3]};
;           o0 = __builtin_amdgcn_mfma_f32_32x32x16_bf16(vf, p, o0, 0, 0, 0); }
;         { const s16x4 lo = vtr(vbase + 4096 + ks * 1024), hh = vtr(vbase + 4096 + ks * 1024 + 512); const bf16x8 vf = {lo[0], lo[1], lo[2], lo[3], hh[0], hh[1], hh[2], hh[3]};
;           o1 = __builtin_amdgcn_mfma_f32_32x32x16_bf16(vf, p, o1, 0, 0, 0); }
;     }
; }
; __device__ __forceinline__ void attn_unit(const bf16_t* Qh, const bf16_t* Kh, const bf16_t* Vh, bf16_t* Oh  , int S, int qb, LAS unsigned char* lds, int tid) {
;     ...
;         {
;             f32x16 p0 = {}, p1 = {};
; #pragma unroll
;             for (int s = 0; s < 6; ++s) {
;                 const bf16x8 a0 = *(const LAS bf16x8*)(lds + cur + kfo + s * 32), a1 = *(const LAS bf16x8*)(lds + cur + kfo + 32 * KPITCH + s * 32);
;                 const bf16x8 q = *(const LAS bf16x8*)(ql + (6 + s) * 1024);
;                 p0 = __builtin_amdgcn_mfma_f32_32x32x16_bf16(a0, q, p0, 0, 0, 0); p1 = __builtin_amdgcn_mfma_f32_32x32x16_bf16(a1, q, p1, 0, 0, 0);
	v_mfma_f32_32x32x16_bf16 v[64:79], v[128:131], v[162:165], v[64:79]
	v_mfma_f32_32x32x16_bf16 v[80:95], v[142:145], v[162:165], v[80:95]
	ds_read_b64_tr_b16 v[128:129], v158 offset:13312
	ds_read_b64_tr_b16 v[130:131], v158 offset:13824
	ds_read_b64_tr_b16 v[142:143], v158 offset:17408
	ds_read_b64_tr_b16 v[144:145], v158 offset:17920
	v_add_f32_e32 v166, v166, v117
	v_add_f32_e32 v141, v141, v118
	v_add_f32_e32 v166, v166, v119
	v_cvt_pk_bf16_f32 v106, v116, v117
	v_cvt_pk_bf16_f32 v107, v118, v119
	v_exp_f32_e32 v124, v124
	v_exp_f32_e32 v125, v125
	v_exp_f32_e32 v126, v126
	v_exp_f32_e32 v127, v127
	s_waitcnt lgkmcnt(4)
	v_mfma_f32_32x32x16_bf16 v[64:79], v[176:179], v[186:189], v[64:79]
	v_mfma_f32_32x32x16_bf16 v[80:95], v[180:183], v[186:189], v[80:95]
	ds_read_b64_tr_b16 v[176:177], v158 offset:14336
	ds_read_b64_tr_b16 v[178:179], v158 offset:14848
	ds_read_b64_tr_b16 v[180:181], v158 offset:18432
	ds_read_b64_tr_b16 v[182:183], v158 offset:18944
	v_add_f32_e32 v141, v141, v120
	v_add_f32_e32 v166, v166, v121
	v_add_f32_e32 v141, v141, v122
	v_add_f32_e32 v166, v166, v123
	v_cvt_pk_bf16_f32 v108, v120, v121
	v_cvt_pk_bf16_f32 v109, v122, v123
	v_add_f32_e32 v141, v141, v124
	v_add_f32_e32 v166, v166, v125
	v_add_f32_e32 v141, v141, v126
	v_add_f32_e32 v166, v166, v127
	v_cvt_pk_bf16_f32 v110, v124, v125
	v_cvt_pk_bf16_f32 v111, v126, v127
	v_add_f32_e32 v141, v141, v166
	s_waitcnt lgkmcnt(4)
	v_mfma_f32_32x32x16_bf16 v[48:63], v[128:131], v[96:99], v[48:63]
	v_mfma_f32_32x32x16_bf16 v[32:47], v[142:145], v[96:99], v[32:47]
	ds_read_b64_tr_b16 v[128:129], v158 offset:15360
	ds_read_b64_tr_b16 v[130:131], v158 offset:15872
	ds_read_b64_tr_b16 v[142:143], v158 offset:19456
	ds_read_b64_tr_b16 v[144:145], v158 offset:19968
	v_max3_f32 v248, v64, v65, v66
	v_max3_f32 v249, v80, v81, v82
	v_max3_f32 v248, v248, v67, v68
	v_max3_f32 v249, v249, v83, v84
	v_max3_f32 v248, v248, v69, v70
	v_max3_f32 v249, v249, v85, v86
	v_max3_f32 v248, v248, v71, v72
	v_max3_f32 v249, v249, v87, v88
	v_max3_f32 v248, v248, v73, v74
	v_max3_f32 v249, v249, v89, v90
	v_max3_f32 v248, v248, v75, v76
	v_max3_f32 v249, v249, v91, v92
	v_max3_f32 v248, v248, v77, v78
	v_max3_f32 v249, v249, v93, v94
	s_waitcnt lgkmcnt(4)
	v_mfma_f32_32x32x16_bf16 v[48:63], v[176:179], v[100:103], v[48:63]
	v_mfma_f32_32x32x16_bf16 v[32:47], v[180:183], v[100:103], v[32:47]
	ds_read_b64_tr_b16 v[176:177], v158 offset:16384
	ds_read_b64_tr_b16 v[178:179], v158 offset:16896
	ds_read_b64_tr_b16 v[180:181], v158 offset:20480
	ds_read_b64_tr_b16 v[182:183], v158 offset:20992
	v_max3_f32 v248, v248, v79, v95
	v_max_f32_e32 v248, v248, v249
	v_mov_b32_e32 v251, v248
	s_nop 1
	v_permlane32_swap_b32_e32 v248, v251
	v_max_f32_e32 v167, v248, v251
	v_cmp_lt_f32_e32 vcc, s72, v167
	s_cbranch_vccnz .Lmla_rescAo
.Lmla_rescAo_back:
	v_exp_f32_e32 v64, v64
	v_exp_f32_e32 v65, v65
	v_exp_f32_e32 v66, v66
	s_waitcnt lgkmcnt(4)
	v_mfma_f32_32x32x16_bf16 v[48:63], v[128:131], v[104:107], v[48:63]
	v_mfma_f32_32x32x16_bf16 v[32:47], v[142:145], v[104:107], v[32:47]
	ds_read_b128 v[128:131], v155 offset:21504
	ds_read_b128 v[142:145], v155 offset:28160
	ds_read_b128 v[162:165], v135 offset:49152
	v_exp_f32_e32 v67, v67
	v_exp_f32_e32 v68, v68
	v_exp_f32_e32 v69, v69
	v_exp_f32_e32 v70, v70
	v_exp_f32_e32 v71, v71
	v_add_f32_e32 v166, v64, v65
	v_add_f32_e32 v140, v140, v66
	v_add_f32_e32 v166, v166, v67
	s_waitcnt lgkmcnt(3)
	v_mfma_f32_32x32x16_bf16 v[48:63], v[176:179], v[108:111], v[48:63]
	v_mfma_f32_32x32x16_bf16 v[32:47], v[180:183], v[108:111], v[32:47]
	ds_read_b128 v[176:179], v155 offset:21536
	ds_read_b128 v[180:183], v155 offset:28192
	ds_read_b128 v[186:189], v135 offset:50176
	v_cvt_pk_bf16_f32 v64, v64, v65
	v_cvt_pk_bf16_f32 v65, v66, v67
	v_exp_f32_e32 v72, v72
	v_exp_f32_e32 v73, v73
	v_exp_f32_e32 v74, v74
	v_exp_f32_e32 v75, v75
	v_add_f32_e32 v140, v140, v68
	v_add_f32_e32 v166, v166, v69
	v_add_f32_e32 v140, v140, v70
	s_waitcnt lgkmcnt(3)
	v_mfma_f32_32x32x16_bf16 v[96:111], v[128:131], v[162:165], v[190:205]
	v_mfma_f32_32x32x16_bf16 v[112:127], v[142:145], v[162:165], v[190:205]
	ds_read_b128 v[128:131], v155 offset:21568
	ds_read_b128 v[142:145], v155 offset:28224
	ds_read_b128 v[162:165], v135 offset:51200
	v_add_f32_e32 v166, v166, v71
	v_cvt_pk_bf16_f32 v66, v68, v69
	v_cvt_pk_bf16_f32 v67, v70, v71
	v_exp_f32_e32 v76, v76
	v_exp_f32_e32 v77, v77
	v_exp_f32_e32 v78, v78
	v_exp_f32_e32 v79, v79
	v_add_f32_e32 v140, v140, v72
	v_add_f32_e32 v166, v166, v73
	s_waitcnt lgkmcnt(3)
	v_mfma_f32_32x32x16_bf16 v[96:111], v[176:179], v[186:189], v[96:111]
	v_mfma_f32_32x32x16_bf16 v[112:127], v[180:183], v[186:189], v[112:127]
	ds_read_b128 v[176:179], v155 offset:21600
	ds_read_b128 v[180:183], v155 offset:28256
	ds_read_b128 v[186:189], v135 offset:52224
	v_add_f32_e32 v140, v140, v74
	v_add_f32_e32 v166, v166, v75
	v_cvt_pk_bf16_f32 v68, v72, v73
	v_cvt_pk_bf16_f32 v69, v74, v75
	v_exp_f32_e32 v80, v80
	v_exp_f32_e32 v81, v81
	v_exp_f32_e32 v82, v82
	v_exp_f32_e32 v83, v83
	v_add_f32_e32 v140, v140, v76
	v_add_f32_e32 v166, v166, v77
	s_waitcnt lgkmcnt(3)
	v_mfma_f32_32x32x16_bf16 v[96:111], v[128:131], v[162:165], v[96:111]
	v_mfma_f32_32x32x16_bf16 v[112:127], v[142:145], v[162:165], v[112:127]
	ds_read_b128 v[128:131], v155 offset:21632
	ds_read_b128 v[142:145], v155 offset:28288
	ds_read_b128 v[162:165], v135 offset:53248
	v_add_f32_e32 v140, v140, v78
	v_add_f32_e32 v166, v166, v79
	v_cvt_pk_bf16_f32 v70, v76, v77
	v_cvt_pk_bf16_f32 v71, v78, v79
	v_exp_f32_e32 v84, v84
	v_exp_f32_e32 v85, v85
	v_exp_f32_e32 v86, v86
	v_exp_f32_e32 v87, v87
	v_add_f32_e32 v140, v140, v80
	s_waitcnt lgkmcnt(3)
; #define LAS __attribute__((address_space(3)))
; __device__ __forceinline__ s16x4 vtr(LAS const unsigned char* p) { return __builtin_bit_cast(s16x4, __builtin_amdgcn_ds_read_tr16_b64_v4i16((LAS s16x4*)p)); }
; __device__ __forceinline__ void softmax_blk(f32x16& p0, f32x16& p1, f32x16& o0, f32x16& o1, float& mhat, float& lrun, u32x4 (&pf)[4], bool first) {
;     ...
;     for (int e = 0; e < 16; ++e) { p0[e] = __builtin_amdgcn_exp2f(p0[e] - mhat); p1[e] = __builtin_amdgcn_exp2f(p1[e] - mhat); s0 += p0[e]; s1 += p1[e]; }
;     lrun += s0 + s1;
;     pf[0] = MLA_PACK(p0, 0); pf[1] = MLA_PACK(p0, 8); pf[2] = MLA_PACK(p1, 0); pf[3] = MLA_PACK(p1, 8);
; }
; __device__ __forceinline__ void pv_blk(const u32x4 (&pf)[4], f32x16& o0, f32x16& o1, LAS const unsigned char* vbase) {
; #pragma unroll
;     for (int ks = 0; ks < 4; ++ks) {
;         const bf16x8 p = __builtin_bit_cast(bf16x8, pf[ks]);
;         { const s16x4 lo = vtr(vbase + ks * 1024), hh = vtr(vbase + ks * 1024 + 512); const bf16x8 vf = {lo[0], lo[1], lo[2], lo[3], hh[0], hh[1], hh[2], hh[3]};
;           o0 = __builtin_amdgcn_mfma_f32_32x32x16_bf16(vf, p, o0, 0, 0, 0); }
;         { const s16x4 lo = vtr(vbase + 4096 + ks * 1024), hh = vtr(vbase + 4096 + ks * 1024 + 512); const bf16x8 vf = {lo[0], lo[1], lo[2], lo[3], hh[0], hh[1], hh[2], hh[3]};
;           o1 = __builtin_amdgcn_mfma_f32_32x32x16_bf16(vf, p, o1, 0, 0, 0); }
;     }
; }
; __device__ __forceinline__ void attn_unit(const bf16_t* Qh, const bf16_t* Kh, const bf16_t* Vh, bf16_t* Oh  , int S, int qb, LAS unsigned char* lds, int tid) {
;     ...
;         {
;             f32x16 p0 = {}, p1 = {};
; #pragma unroll
;             for (int s = 0; s < 6; ++s) {
;                 const bf16x8 a0 = *(const LAS bf16x8*)(lds + cur + kfo + s * 32), a1 = *(const LAS bf16x8*)(lds + cur + kfo + 32 * KPITCH + s * 32);
;                 const bf16x8 q = *(const LAS bf16x8*)(ql + (6 + s) * 1024);
;                 p0 = __builtin_amdgcn_mfma_f32_32x32x16_bf16(a0, q, p0, 0, 0, 0); p1 = __builtin_amdgcn_mfma_f32_32x32x16_bf16(a1, q, p1, 0, 0, 0);
;             }
;             softmax_blk(p0, p1, ob0, ob1, mb, lb, pf, t == 0);
;             pv_blk(pf, ob0, ob1, lds + cur + vb);
;         }
;         *(LAS u32x4*)(lds + nxt + kd0) = ka; *(LAS u32x4*)(lds + (has1 ? nxt : 0u) + kd1) = kb; *(LAS u32x4*)(lds + nxt + vd) = va;
;         __syncthreads();
	v_mfma_f32_32x32x16_bf16 v[96:111], v[176:179], v[186:189], v[96:111]
	v_mfma_f32_32x32x16_bf16 v[112:127], v[180:183], v[186:189], v[112:127]
	ds_read_b128 v[176:179], v155 offset:21664
	ds_read_b128 v[180:183], v155 offset:28320
	ds_read_b128 v[186:189], v135 offset:54272
	v_add_f32_e32 v166, v166, v81
	v_add_f32_e32 v140, v140, v82
	v_add_f32_e32 v166, v166, v83
	v_cvt_pk_bf16_f32 v72, v80, v81
	v_cvt_pk_bf16_f32 v73, v82, v83
	v_exp_f32_e32 v88, v88
	v_exp_f32_e32 v89, v89
	v_exp_f32_e32 v90, v90
	v_exp_f32_e32 v91, v91
	v_add_f32_e32 v140, v140, v84
	s_waitcnt vmcnt(0)
	ds_write_b128 v150, v[218:221]
	ds_write_b128 v156, v[222:225]
	ds_write_b128 v157, v[226:229] offset:34816
	s_waitcnt lgkmcnt(6)
	v_mfma_f32_32x32x16_bf16 v[96:111], v[128:131], v[162:165], v[96:111]
	v_mfma_f32_32x32x16_bf16 v[112:127], v[142:145], v[162:165], v[112:127]
	v_add_f32_e32 v166, v166, v85
	v_add_f32_e32 v140, v140, v86
	v_add_f32_e32 v166, v166, v87
	v_cvt_pk_bf16_f32 v74, v84, v85
	v_cvt_pk_bf16_f32 v75, v86, v87
	v_exp_f32_e32 v92, v92
	v_exp_f32_e32 v93, v93
	v_exp_f32_e32 v94, v94
	v_exp_f32_e32 v95, v95
	s_waitcnt lgkmcnt(3)
	v_mfma_f32_32x32x16_bf16 v[96:111], v[176:179], v[186:189], v[96:111]
	v_mfma_f32_32x32x16_bf16 v[112:127], v[180:183], v[186:189], v[112:127]
	v_add_f32_e32 v140, v140, v88
	v_add_f32_e32 v166, v166, v89
	v_add_f32_e32 v140, v140, v90
	v_add_f32_e32 v166, v166, v91
	v_cvt_pk_bf16_f32 v76, v88, v89
	v_cvt_pk_bf16_f32 v77, v90, v91
	v_add_f32_e32 v140, v140, v92
	v_add_f32_e32 v166, v166, v93
	v_add_f32_e32 v140, v140, v94
	v_add_f32_e32 v166, v166, v95
	v_cvt_pk_bf16_f32 v78, v92, v93
	v_cvt_pk_bf16_f32 v79, v94, v95
	v_add_f32_e32 v140, v140, v166
	s_waitcnt lgkmcnt(0)
	s_barrier
	s_add_i32 s1, s1, 1
	s_cmp_lg_u32 s1, s18
	s_cbranch_scc0 .Lmla_epi
	ds_read_b64_tr_b16 v[128:129], v158 offset:34816
	ds_read_b64_tr_b16 v[130:131], v158 offset:35328
	ds_read_b64_tr_b16 v[142:143], v158 offset:38912
	ds_read_b64_tr_b16 v[144:145], v158 offset:39424
	ds_read_b64_tr_b16 v[176:177], v158 offset:35840
	ds_read_b64_tr_b16 v[178:179], v158 offset:36352
	ds_read_b64_tr_b16 v[180:181], v158 offset:39936
	ds_read_b64_tr_b16 v[182:183], v158 offset:40448
	s_waitcnt lgkmcnt(4)
	v_mfma_f32_32x32x16_bf16 v[16:31], v[128:131], v[64:67], v[16:31]
	v_mfma_f32_32x32x16_bf16 v[0:15], v[142:145], v[64:67], v[0:15]
	ds_read_b64_tr_b16 v[128:129], v158 offset:36864
	ds_read_b64_tr_b16 v[130:131], v158 offset:37376
	ds_read_b64_tr_b16 v[142:143], v158 offset:40960
	ds_read_b64_tr_b16 v[144:145], v158 offset:41472
	global_load_dwordx4 v[218:221], v171, s[26:27]
	global_load_dwordx4 v[222:225], v184, s[26:27]
	global_load_dwordx4 v[226:229], v146, s[100:101]
	s_add_u32 s26, s26, 0x3000
	s_addc_u32 s27, s27, 0
	s_add_u32 s100, s100, 0x2000
	s_addc_u32 s101, s101, 0
	v_max3_f32 v248, v96, v97, v98
	v_max3_f32 v249, v112, v113, v114
	v_max3_f32 v248, v248, v99, v100
	v_max3_f32 v249, v249, v115, v116
	v_max3_f32 v248, v248, v101, v102
	v_max3_f32 v249, v249, v117, v118
	v_max3_f32 v248, v248, v103, v104
	v_max3_f32 v249, v249, v119, v120
	v_max3_f32 v248, v248, v105, v106
	v_max3_f32 v249, v249, v121, v122
	v_max3_f32 v248, v248, v107, v108
	v_max3_f32 v249, v249, v123, v124
	v_max3_f32 v248, v248, v109, v110
	v_max3_f32 v249, v249, v125, v126
	s_waitcnt lgkmcnt(4)
	v_mfma_f32_32x32x16_bf16 v[16:31], v[176:179], v[68:71], v[16:31]
	v_mfma_f32_32x32x16_bf16 v[0:15], v[180:183], v[68:71], v[0:15]
	ds_read_b64_tr_b16 v[176:177], v158 offset:37888
	ds_read_b64_tr_b16 v[178:179], v158 offset:38400
	ds_read_b64_tr_b16 v[180:181], v158 offset:41984
	ds_read_b64_tr_b16 v[182:183], v158 offset:42496
	v_max3_f32 v248, v248, v111, v127
	v_max_f32_e32 v248, v248, v249
	v_mov_b32_e32 v251, v248
	s_nop 1
	v_permlane32_swap_b32_e32 v248, v251
	v_max_f32_e32 v167, v248, v251
	v_cmp_lt_f32_e32 vcc, s72, v167
	s_cbranch_vccnz .Lmla_rescBv
.Lmla_rescBv_back:
	v_exp_f32_e32 v96, v96
	v_exp_f32_e32 v97, v97
	v_exp_f32_e32 v98, v98
	s_waitcnt lgkmcnt(4)
	v_mfma_f32_32x32x16_bf16 v[16:31], v[128:131], v[72:75], v[16:31]
	v_mfma_f32_32x32x16_bf16 v[0:15], v[142:145], v[72:75], v[0:15]
	ds_read_b128 v[128:131], v155
	ds_read_b128 v[142:145], v155 offset:6656
	ds_read_b128 v[162:165], v135 offset:43008
	v_exp_f32_e32 v99, v99
	v_exp_f32_e32 v100, v100
	v_exp_f32_e32 v101, v101
	v_exp_f32_e32 v102, v102
	v_exp_f32_e32 v103, v103
	v_add_f32_e32 v166, v96, v97
	v_add_f32_e32 v141, v141, v98
	v_add_f32_e32 v166, v166, v99
	s_waitcnt lgkmcnt(3)
	v_mfma_f32_32x32x16_bf16 v[16:31], v[176:179], v[76:79], v[16:31]
	v_mfma_f32_32x32x16_bf16 v[0:15], v[180:183], v[76:79], v[0:15]
	ds_read_b128 v[176:179], v155 offset:32
	ds_read_b128 v[180:183], v155 offset:6688
	ds_read_b128 v[186:189], v135 offset:44032
	v_cvt_pk_bf16_f32 v96, v96, v97
	v_cvt_pk_bf16_f32 v97, v98, v99
	v_exp_f32_e32 v104, v104
	v_exp_f32_e32 v105, v105
	v_exp_f32_e32 v106, v106
	v_exp_f32_e32 v107, v107
	v_add_f32_e32 v141, v141, v100
	v_add_f32_e32 v166, v166, v101
	v_add_f32_e32 v141, v141, v102
	s_waitcnt lgkmcnt(3)
	v_mfma_f32_32x32x16_bf16 v[64:79], v[128:131], v[162:165], v[232:247]
	v_mfma_f32_32x32x16_bf16 v[80:95], v[142:145], v[162:165], v[232:247]
	ds_read_b128 v[128:131], v155 offset:64
	ds_read_b128 v[142:145], v155 offset:6720
	ds_read_b128 v[162:165], v135 offset:45056
	v_add_f32_e32 v166, v166, v103
	v_cvt_pk_bf16_f32 v98, v100, v101
	v_cvt_pk_bf16_f32 v99, v102, v103
	v_exp_f32_e32 v108, v108
	v_exp_f32_e32 v109, v109
	v_exp_f32_e32 v110, v110
	v_exp_f32_e32 v111, v111
	v_add_f32_e32 v141, v141, v104
	v_add_f32_e32 v166, v166, v105
	s_waitcnt lgkmcnt(3)
; __device__ __forceinline__ void softmax_blk(f32x16& p0, f32x16& p1, f32x16& o0, f32x16& o1, float& mhat, float& lrun, u32x4 (&pf)[4], bool first) {
;     float r0 = max2_(p0[0], p0[1]), r1 = max2_(p1[0], p1[1]);
; #pragma unroll
;     for (int e = 2; e < 16; ++e) { r0 = max2_(r0, p0[e]); r1 = max2_(r1, p1[e]); }
;     const float rm = swap_max(max2_(r0, r1));
;     if (first || __any(rm - mhat > THR)) {
;         const float mn = first ? rm : fmaxf(rm, mhat); const float f = first ? 0.f : __builtin_amdgcn_exp2f(mhat - mn); mhat = mn; lrun *= f;
; #pragma unroll
;         for (int e = 0; e < 16; ++e) { o0[e] *= f; o1[e] *= f; }
;     }
;     float s0 = 0.f, s1 = 0.f;
; #pragma unroll
;     for (int e = 0; e < 16; ++e) { p0[e] = __builtin_amdgcn_exp2f(p0[e] - mhat); p1[e] = __builtin_amdgcn_exp2f(p1[e] - mhat); s0 += p0[e]; s1 += p1[e]; }
;     lrun += s0 + s1;
;     pf[0] = MLA_PACK(p0, 0); pf[1] = MLA_PACK(p0, 8); pf[2] = MLA_PACK(p1, 0); pf[3] = MLA_PACK(p1, 8);
; }
; __device__ __forceinline__ void pv_blk(const u32x4 (&pf)[4], f32x16& o0, f32x16& o1, LAS const unsigned char* vbase) {
; #pragma unroll
;     for (int ks = 0; ks < 4; ++ks) {
;         const bf16x8 p = __builtin_bit_cast(bf16x8, pf[ks]);
;         { const s16x4 lo = vtr(vbase + ks * 1024), hh = vtr(vbase + ks * 1024 + 512); const bf16x8 vf = {lo[0], lo[1], lo[2], lo[3], hh[0], hh[1], hh[2], hh[3]};
;           o0 = __builtin_amdgcn_mfma_f32_32x32x16_bf16(vf, p, o0, 0, 0, 0); }
;         { const s16x4 lo = vtr(vbase + 4096 + ks * 1024), hh = vtr(vbase + 4096 + ks * 1024 + 512); const bf16x8 vf = {lo[0], lo[1], lo[2], lo[3], hh[0], hh[1], hh[2], hh[3]};
;           o1 = __builtin_amdgcn_mfma_f32_32x32x16_bf16(vf, p, o1, 0, 0, 0); }
;     }
; }
; __device__ __forceinline__ void attn_unit(const bf16_t* Qh, const bf16_t* Kh, const bf16_t* Vh, bf16_t* Oh  , int S, int qb, LAS unsigned char* lds, int tid) {
;     ...
;         {
;             f32x16 p0 = {}, p1 = {};
; #pragma unroll
;             for (int s = 0; s < 6; ++s) {
;                 const bf16x8 a0 = *(const LAS bf16x8*)(lds + cur + kfo + s * 32), a1 = *(const LAS bf16x8*)(lds + cur + kfo + 32 * KPITCH + s * 32);
;                 const bf16x8 q = *(const LAS bf16x8*)(ql + (6 + s) * 1024);
;                 p0 = __builtin_amdgcn_mfma_f32_32x32x16_bf16(a0, q, p0, 0, 0, 0); p1 = __builtin_amdgcn_mfma_f32_32x32x16_bf16(a1, q, p1, 0, 0, 0);
	v_mfma_f32_32x32x16_bf16 v[64:79], v[176:179], v[186:189], v[64:79]
	v_mfma_f32_32x32x16_bf16 v[80:95], v[180:183], v[186:189], v[80:95]
	ds_read_b128 v[176:179], v155 offset:96
	ds_read_b128 v[180:183], v155 offset:6752
	ds_read_b128 v[186:189], v135 offset:46080
	v_add_f32_e32 v141, v141, v106
	v_add_f32_e32 v166, v166, v107
	v_cvt_pk_bf16_f32 v100, v104, v105
	v_cvt_pk_bf16_f32 v101, v106, v107
	v_exp_f32_e32 v112, v112
	v_exp_f32_e32 v113, v113
	v_exp_f32_e32 v114, v114
	v_exp_f32_e32 v115, v115
	v_add_f32_e32 v141, v141, v108
	v_add_f32_e32 v166, v166, v109
	s_waitcnt lgkmcnt(3)
	v_mfma_f32_32x32x16_bf16 v[64:79], v[128:131], v[162:165], v[64:79]
	v_mfma_f32_32x32x16_bf16 v[80:95], v[142:145], v[162:165], v[80:95]
	ds_read_b128 v[128:131], v155 offset:128
	ds_read_b128 v[142:145], v155 offset:6784
	ds_read_b128 v[162:165], v135 offset:47104
	v_add_f32_e32 v141, v141, v110
	v_add_f32_e32 v166, v166, v111
	v_cvt_pk_bf16_f32 v102, v108, v109
	v_cvt_pk_bf16_f32 v103, v110, v111
	v_exp_f32_e32 v116, v116
	v_exp_f32_e32 v117, v117
	v_exp_f32_e32 v118, v118
	v_exp_f32_e32 v119, v119
	v_add_f32_e32 v141, v141, v112
	s_waitcnt lgkmcnt(3)
	v_mfma_f32_32x32x16_bf16 v[64:79], v[176:179], v[186:189], v[64:79]
	v_mfma_f32_32x32x16_bf16 v[80:95], v[180:183], v[186:189], v[80:95]
	ds_read_b128 v[176:179], v155 offset:160
	ds_read_b128 v[180:183], v155 offset:6816
	ds_read_b128 v[186:189], v135 offset:48128
	v_add_f32_e32 v166, v166, v113
	v_add_f32_e32 v141, v141, v114
	v_add_f32_e32 v166, v166, v115
	v_cvt_pk_bf16_f32 v104, v112, v113
	v_cvt_pk_bf16_f32 v105, v114, v115
	v_exp_f32_e32 v120, v120
	v_exp_f32_e32 v121, v121
	v_exp_f32_e32 v122, v122
	v_exp_f32_e32 v123, v123
	v_add_f32_e32 v141, v141, v116
	s_waitcnt lgkmcnt(3)
	v_mfma_f32_32x32x16_bf16 v[64:79], v[128:131], v[162:165], v[64:79]
	v_mfma_f32_32x32x16_bf16 v[80:95], v[142:145], v[162:165], v[80:95]
	ds_read_b64_tr_b16 v[128:129], v158 offset:34816
	ds_read_b64_tr_b16 v[130:131], v158 offset:35328
	ds_read_b64_tr_b16 v[142:143], v158 offset:38912
	ds_read_b64_tr_b16 v[144:145], v158 offset:39424
	v_add_f32_e32 v166, v166, v117
	v_add_f32_e32 v141, v141, v118
	v_add_f32_e32 v166, v166, v119
	v_cvt_pk_bf16_f32 v106, v116, v117
	v_cvt_pk_bf16_f32 v107, v118, v119
	v_exp_f32_e32 v124, v124
	v_exp_f32_e32 v125, v125
	v_exp_f32_e32 v126, v126
	v_exp_f32_e32 v127, v127
	s_waitcnt lgkmcnt(4)
	v_mfma_f32_32x32x16_bf16 v[64:79], v[176:179], v[186:189], v[64:79]
	v_mfma_f32_32x32x16_bf16 v[80:95], v[180:183], v[186:189], v[80:95]
	ds_read_b64_tr_b16 v[176:177], v158 offset:35840
	ds_read_b64_tr_b16 v[178:179], v158 offset:36352
	ds_read_b64_tr_b16 v[180:181], v158 offset:39936
	ds_read_b64_tr_b16 v[182:183], v158 offset:40448
	v_add_f32_e32 v141, v141, v120
	v_add_f32_e32 v166, v166, v121
	v_add_f32_e32 v141, v141, v122
	v_add_f32_e32 v166, v166, v123
	v_cvt_pk_bf16_f32 v108, v120, v121
	v_cvt_pk_bf16_f32 v109, v122, v123
	v_add_f32_e32 v141, v141, v124
	v_add_f32_e32 v166, v166, v125
	v_add_f32_e32 v141, v141, v126
	v_add_f32_e32 v166, v166, v127
	v_cvt_pk_bf16_f32 v110, v124, v125
	v_cvt_pk_bf16_f32 v111, v126, v127
	v_add_f32_e32 v141, v141, v166
	s_waitcnt lgkmcnt(4)
	v_mfma_f32_32x32x16_bf16 v[48:63], v[128:131], v[96:99], v[48:63]
	v_mfma_f32_32x32x16_bf16 v[32:47], v[142:145], v[96:99], v[32:47]
	ds_read_b64_tr_b16 v[128:129], v158 offset:36864
	ds_read_b64_tr_b16 v[130:131], v158 offset:37376
	ds_read_b64_tr_b16 v[142:143], v158 offset:40960
	ds_read_b64_tr_b16 v[144:145], v158 offset:41472
	v_max3_f32 v248, v64, v65, v66
	v_max3_f32 v249, v80, v81, v82
	v_max3_f32 v248, v248, v67, v68
	v_max3_f32 v249, v249, v83, v84
	v_max3_f32 v248, v248, v69, v70
	v_max3_f32 v249, v249, v85, v86
	v_max3_f32 v248, v248, v71, v72
	v_max3_f32 v249, v249, v87, v88
	v_max3_f32 v248, v248, v73, v74
	v_max3_f32 v249, v249, v89, v90
	v_max3_f32 v248, v248, v75, v76
	v_max3_f32 v249, v249, v91, v92
	v_max3_f32 v248, v248, v77, v78
	v_max3_f32 v249, v249, v93, v94
	s_waitcnt lgkmcnt(4)
	v_mfma_f32_32x32x16_bf16 v[48:63], v[176:179], v[100:103], v[48:63]
	v_mfma_f32_32x32x16_bf16 v[32:47], v[180:183], v[100:103], v[32:47]
	ds_read_b64_tr_b16 v[176:177], v158 offset:37888
	ds_read_b64_tr_b16 v[178:179], v158 offset:38400
	ds_read_b64_tr_b16 v[180:181], v158 offset:41984
	ds_read_b64_tr_b16 v[182:183], v158 offset:42496
	v_max3_f32 v248, v248, v79, v95
	v_max_f32_e32 v248, v248, v249
	v_mov_b32_e32 v251, v248
	s_nop 1
	v_permlane32_swap_b32_e32 v248, v251
	v_max_f32_e32 v167, v248, v251
	v_cmp_lt_f32_e32 vcc, s72, v167
	s_cbranch_vccnz .Lmla_rescAe
; #define LAS __attribute__((address_space(3)))
; __device__ __forceinline__ s16x4 vtr(LAS const unsigned char* p) { return __builtin_bit_cast(s16x4, __builtin_amdgcn_ds_read_tr16_b64_v4i16((LAS s16x4*)p)); }
; __device__ __forceinline__ void softmax_blk(f32x16& p0, f32x16& p1, f32x16& o0, f32x16& o1, float& mhat, float& lrun, u32x4 (&pf)[4], bool first) {
;     ...
;     for (int e = 0; e < 16; ++e) { p0[e] = __builtin_amdgcn_exp2f(p0[e] - mhat); p1[e] = __builtin_amdgcn_exp2f(p1[e] - mhat); s0 += p0[e]; s1 += p1[e]; }
;     lrun += s0 + s1;
;     pf[0] = MLA_PACK(p0, 0); pf[1] = MLA_PACK(p0, 8); pf[2] = MLA_PACK(p1, 0); pf[3] = MLA_PACK(p1, 8);
; }
; __device__ __forceinline__ void pv_blk(const u32x4 (&pf)[4], f32x16& o0, f32x16& o1, LAS const unsigned char* vbase) {
; #pragma unroll
;     for (int ks = 0; ks < 4; ++ks) {
;         const bf16x8 p = __builtin_bit_cast(bf16x8, pf[ks]);
;         { const s16x4 lo = vtr(vbase + ks * 1024), hh = vtr(vbase + ks * 1024 + 512); const bf16x8 vf = {lo[0], lo[1], lo[2], lo[3], hh[0], hh[1], hh[2], hh[3]};
;           o0 = __builtin_amdgcn_mfma_f32_32x32x16_bf16(vf, p, o0, 0, 0, 0); }
;         { const s16x4 lo = vtr(vbase + 4096 + ks * 1024), hh = vtr(vbase + 4096 + ks * 1024 + 512); const bf16x8 vf = {lo[0], lo[1], lo[2], lo[3], hh[0], hh[1], hh[2], hh[3]};
;           o1 = __builtin_amdgcn_mfma_f32_32x32x16_bf16(vf, p, o1, 0, 0, 0); }
;     }
; }
; __device__ __forceinline__ void attn_unit(const bf16_t* Qh, const bf16_t* Kh, const bf16_t* Vh, bf16_t* Oh  , int S, int qb, LAS unsigned char* lds, int tid) {
;     ...
;         {
;             f32x16 p0 = {}, p1 = {};
; #pragma unroll
;             for (int s = 0; s < 6; ++s) {
;                 const bf16x8 a0 = *(const LAS bf16x8*)(lds + cur + kfo + s * 32), a1 = *(const LAS bf16x8*)(lds + cur + kfo + 32 * KPITCH + s * 32);
;                 const bf16x8 q = *(const LAS bf16x8*)(ql + (6 + s) * 1024);
;                 p0 = __builtin_amdgcn_mfma_f32_32x32x16_bf16(a0, q, p0, 0, 0, 0); p1 = __builtin_amdgcn_mfma_f32_32x32x16_bf16(a1, q, p1, 0, 0, 0);
;             }
;             softmax_blk(p0, p1, ob0, ob1, mb, lb, pf, t == 0);
;             pv_blk(pf, ob0, ob1, lds + cur + vb);
;         }
;         *(LAS u32x4*)(lds + nxt + kd0) = ka; *(LAS u32x4*)(lds + (has1 ? nxt : 0u) + kd1) = kb; *(LAS u32x4*)(lds + nxt + vd) = va;
;         __syncthreads();
.Lmla_rescAe_back:
	v_exp_f32_e32 v64, v64
	v_exp_f32_e32 v65, v65
	v_exp_f32_e32 v66, v66
	s_waitcnt lgkmcnt(4)
	v_mfma_f32_32x32x16_bf16 v[48:63], v[128:131], v[104:107], v[48:63]
	v_mfma_f32_32x32x16_bf16 v[32:47], v[142:145], v[104:107], v[32:47]
	ds_read_b128 v[128:131], v155
	ds_read_b128 v[142:145], v155 offset:6656
	ds_read_b128 v[162:165], v135 offset:49152
	v_exp_f32_e32 v67, v67
	v_exp_f32_e32 v68, v68
	v_exp_f32_e32 v69, v69
	v_exp_f32_e32 v70, v70
	v_exp_f32_e32 v71, v71
	v_add_f32_e32 v166, v64, v65
	v_add_f32_e32 v140, v140, v66
	v_add_f32_e32 v166, v166, v67
	s_waitcnt lgkmcnt(3)
	v_mfma_f32_32x32x16_bf16 v[48:63], v[176:179], v[108:111], v[48:63]
	v_mfma_f32_32x32x16_bf16 v[32:47], v[180:183], v[108:111], v[32:47]
	ds_read_b128 v[176:179], v155 offset:32
	ds_read_b128 v[180:183], v155 offset:6688
	ds_read_b128 v[186:189], v135 offset:50176
	v_cvt_pk_bf16_f32 v64, v64, v65
	v_cvt_pk_bf16_f32 v65, v66, v67
	v_exp_f32_e32 v72, v72
	v_exp_f32_e32 v73, v73
	v_exp_f32_e32 v74, v74
	v_exp_f32_e32 v75, v75
	v_add_f32_e32 v140, v140, v68
	v_add_f32_e32 v166, v166, v69
	v_add_f32_e32 v140, v140, v70
	s_waitcnt lgkmcnt(3)
	v_mfma_f32_32x32x16_bf16 v[96:111], v[128:131], v[162:165], v[190:205]
	v_mfma_f32_32x32x16_bf16 v[112:127], v[142:145], v[162:165], v[190:205]
	ds_read_b128 v[128:131], v155 offset:64
	ds_read_b128 v[142:145], v155 offset:6720
	ds_read_b128 v[162:165], v135 offset:51200
	v_add_f32_e32 v166, v166, v71
	v_cvt_pk_bf16_f32 v66, v68, v69
	v_cvt_pk_bf16_f32 v67, v70, v71
	v_exp_f32_e32 v76, v76
	v_exp_f32_e32 v77, v77
	v_exp_f32_e32 v78, v78
	v_exp_f32_e32 v79, v79
	v_add_f32_e32 v140, v140, v72
	v_add_f32_e32 v166, v166, v73
	s_waitcnt lgkmcnt(3)
	v_mfma_f32_32x32x16_bf16 v[96:111], v[176:179], v[186:189], v[96:111]
	v_mfma_f32_32x32x16_bf16 v[112:127], v[180:183], v[186:189], v[112:127]
	ds_read_b128 v[176:179], v155 offset:96
	ds_read_b128 v[180:183], v155 offset:6752
	ds_read_b128 v[186:189], v135 offset:52224
	v_add_f32_e32 v140, v140, v74
	v_add_f32_e32 v166, v166, v75
	v_cvt_pk_bf16_f32 v68, v72, v73
	v_cvt_pk_bf16_f32 v69, v74, v75
	v_exp_f32_e32 v80, v80
	v_exp_f32_e32 v81, v81
	v_exp_f32_e32 v82, v82
	v_exp_f32_e32 v83, v83
	v_add_f32_e32 v140, v140, v76
	v_add_f32_e32 v166, v166, v77
	s_waitcnt lgkmcnt(3)
	v_mfma_f32_32x32x16_bf16 v[96:111], v[128:131], v[162:165], v[96:111]
	v_mfma_f32_32x32x16_bf16 v[112:127], v[142:145], v[162:165], v[112:127]
	ds_read_b128 v[128:131], v155 offset:128
	ds_read_b128 v[142:145], v155 offset:6784
	ds_read_b128 v[162:165], v135 offset:53248
	v_add_f32_e32 v140, v140, v78
	v_add_f32_e32 v166, v166, v79
	v_cvt_pk_bf16_f32 v70, v76, v77
	v_cvt_pk_bf16_f32 v71, v78, v79
	v_exp_f32_e32 v84, v84
	v_exp_f32_e32 v85, v85
	v_exp_f32_e32 v86, v86
	v_exp_f32_e32 v87, v87
	v_add_f32_e32 v140, v140, v80
	s_waitcnt lgkmcnt(3)
	v_mfma_f32_32x32x16_bf16 v[96:111], v[176:179], v[186:189], v[96:111]
	v_mfma_f32_32x32x16_bf16 v[112:127], v[180:183], v[186:189], v[112:127]
	ds_read_b128 v[176:179], v155 offset:160
	ds_read_b128 v[180:183], v155 offset:6816
	ds_read_b128 v[186:189], v135 offset:54272
	v_add_f32_e32 v166, v166, v81
	v_add_f32_e32 v140, v140, v82
	v_add_f32_e32 v166, v166, v83
	v_cvt_pk_bf16_f32 v72, v80, v81
	v_cvt_pk_bf16_f32 v73, v82, v83
	v_exp_f32_e32 v88, v88
	v_exp_f32_e32 v89, v89
	v_exp_f32_e32 v90, v90
	v_exp_f32_e32 v91, v91
	v_add_f32_e32 v140, v140, v84
	s_waitcnt vmcnt(0)
	ds_write_b128 v150, v[218:221] offset:21504
	ds_write_b128 v159, v[222:225]
	ds_write_b128 v157, v[226:229] offset:13312
	s_waitcnt lgkmcnt(6)
	v_mfma_f32_32x32x16_bf16 v[96:111], v[128:131], v[162:165], v[96:111]
	v_mfma_f32_32x32x16_bf16 v[112:127], v[142:145], v[162:165], v[112:127]
	v_add_f32_e32 v166, v166, v85
	v_add_f32_e32 v140, v140, v86
	v_add_f32_e32 v166, v166, v87
	v_cvt_pk_bf16_f32 v74, v84, v85
	v_cvt_pk_bf16_f32 v75, v86, v87
	v_exp_f32_e32 v92, v92
	v_exp_f32_e32 v93, v93
	v_exp_f32_e32 v94, v94
	v_exp_f32_e32 v95, v95
	s_waitcnt lgkmcnt(3)
	v_mfma_f32_32x32x16_bf16 v[96:111], v[176:179], v[186:189], v[96:111]
	v_mfma_f32_32x32x16_bf16 v[112:127], v[180:183], v[186:189], v[112:127]
	v_add_f32_e32 v140, v140, v88
	v_add_f32_e32 v166, v166, v89
	v_add_f32_e32 v140, v140, v90
	v_add_f32_e32 v166, v166, v91
	v_cvt_pk_bf16_f32 v76, v88, v89
	v_cvt_pk_bf16_f32 v77, v90, v91
	v_add_f32_e32 v140, v140, v92
	v_add_f32_e32 v166, v166, v93
	v_add_f32_e32 v140, v140, v94
	v_add_f32_e32 v166, v166, v95
	v_cvt_pk_bf16_f32 v78, v92, v93
	v_cvt_pk_bf16_f32 v79, v94, v95
	v_add_f32_e32 v140, v140, v166
	s_waitcnt lgkmcnt(0)
	s_barrier
	s_add_i32 s1, s1, 1
	s_branch .Lmla_top

; #define LAS __attribute__((address_space(3)))
; __device__ __forceinline__ float swap_max(float m) { auto rr = __builtin_amdgcn_permlane32_swap(__float_as_uint(m), __float_as_uint(m), false, false); return fmaxf(__uint_as_float(rr[0]), __uint_as_float(rr[1])); }
; __device__ __forceinline__ float max2_(float a, float b) { return __builtin_amdgcn_fmed3f(a, b, INFINITY); }
; __device__ __forceinline__ void softmax_blk(f32x16& p0, f32x16& p1, f32x16& o0, f32x16& o1, float& mhat, float& lrun, u32x4 (&pf)[4], bool first) {
;     float r0 = max2_(p0[0], p0[1]), r1 = max2_(p1[0], p1[1]);
; #pragma unroll
;     for (int e = 2; e < 16; ++e) { r0 = max2_(r0, p0[e]); r1 = max2_(r1, p1[e]); }
;     const float rm = swap_max(max2_(r0, r1));
;     if (first || __any(rm - mhat > THR)) {
;         const float mn = first ? rm : fmaxf(rm, mhat); const float f = first ? 0.f : __builtin_amdgcn_exp2f(mhat - mn); mhat = mn; lrun *= f;
; #pragma unroll
;         for (int e = 0; e < 16; ++e) { o0[e] *= f; o1[e] *= f; }
;     }
;     float s0 = 0.f, s1 = 0.f;
; #pragma unroll
;     for (int e = 0; e < 16; ++e) { p0[e] = __builtin_amdgcn_exp2f(p0[e] - mhat); p1[e] = __builtin_amdgcn_exp2f(p1[e] - mhat); s0 += p0[e]; s1 += p1[e]; }
;     lrun += s0 + s1;
;     pf[0] = MLA_PACK(p0, 0); pf[1] = MLA_PACK(p0, 8); pf[2] = MLA_PACK(p1, 0); pf[3] = MLA_PACK(p1, 8);
; }
; __device__ __forceinline__ void pv_blk(const u32x4 (&pf)[4], f32x16& o0, f32x16& o1, LAS const unsigned char* vbase) {
; #pragma unroll
;     for (int ks = 0; ks < 4; ++ks) {
;         const bf16x8 p = __builtin_bit_cast(bf16x8, pf[ks]);
;         { const s16x4 lo = vtr(vbase + ks * 1024), hh = vtr(vbase + ks * 1024 + 512); const bf16x8 vf = {lo[0], lo[1], lo[2], lo[3], hh[0], hh[1], hh[2], hh[3]};
;           o0 = __builtin_amdgcn_mfma_f32_32x32x16_bf16(vf, p, o0, 0, 0, 0); }
;         { const s16x4 lo = vtr(vbase + 4096 + ks * 1024), hh = vtr(vbase + 4096 + ks * 1024 + 512); const bf16x8 vf = {lo[0], lo[1], lo[2], lo[3], hh[0], hh[1], hh[2], hh[3]};
;           o1 = __builtin_amdgcn_mfma_f32_32x32x16_bf16(vf, p, o1, 0, 0, 0); }
;     }
; }
; __device__ __forceinline__ void attn_unit(const bf16_t* Qh, const bf16_t* Kh, const bf16_t* Vh, bf16_t* Oh  , int S, int qb, LAS unsigned char* lds, int tid) {
;     ...
;             softmax_blk(p0, p1, ob0, ob1, mb, lb, pf, t == 0);
;             pv_blk(pf, ob0, ob1, lds + cur + vb);
.Lmla_rescBe_back:
	v_exp_f32_e32 v96, v96
	v_exp_f32_e32 v97, v97
	v_exp_f32_e32 v98, v98
	v_exp_f32_e32 v99, v99
	v_exp_f32_e32 v100, v100
	v_exp_f32_e32 v101, v101
	s_waitcnt lgkmcnt(4)
	v_mfma_f32_32x32x16_bf16 v[16:31], v[176:179], v[68:71], v[16:31]
	v_mfma_f32_32x32x16_bf16 v[0:15], v[180:183], v[68:71], v[0:15]
	ds_read_b64_tr_b16 v[176:177], v158 offset:37888
	ds_read_b64_tr_b16 v[178:179], v158 offset:38400
	ds_read_b64_tr_b16 v[180:181], v158 offset:41984
	ds_read_b64_tr_b16 v[182:183], v158 offset:42496
	v_exp_f32_e32 v102, v102
	v_exp_f32_e32 v103, v103
	v_add_f32_e32 v166, v96, v97
	v_add_f32_e32 v141, v141, v98
	v_add_f32_e32 v166, v166, v99
	v_cvt_pk_bf16_f32 v96, v96, v97
	v_cvt_pk_bf16_f32 v97, v98, v99
	v_exp_f32_e32 v104, v104
	v_exp_f32_e32 v105, v105
	v_exp_f32_e32 v106, v106
	v_exp_f32_e32 v107, v107
	v_add_f32_e32 v141, v141, v100
	v_add_f32_e32 v166, v166, v101
	v_add_f32_e32 v141, v141, v102
	v_add_f32_e32 v166, v166, v103
	v_cvt_pk_bf16_f32 v98, v100, v101
	v_cvt_pk_bf16_f32 v99, v102, v103
	v_exp_f32_e32 v108, v108
	v_exp_f32_e32 v109, v109
	v_exp_f32_e32 v110, v110
	v_exp_f32_e32 v111, v111
	v_add_f32_e32 v141, v141, v104
	v_add_f32_e32 v166, v166, v105
	s_waitcnt lgkmcnt(4)
	v_mfma_f32_32x32x16_bf16 v[16:31], v[128:131], v[72:75], v[16:31]
	v_mfma_f32_32x32x16_bf16 v[0:15], v[142:145], v[72:75], v[0:15]
	ds_read_b64_tr_b16 v[128:129], v158 offset:34816
	ds_read_b64_tr_b16 v[130:131], v158 offset:35328
	ds_read_b64_tr_b16 v[142:143], v158 offset:38912
	ds_read_b64_tr_b16 v[144:145], v158 offset:39424
	v_add_f32_e32 v141, v141, v106
	v_add_f32_e32 v166, v166, v107
	v_cvt_pk_bf16_f32 v100, v104, v105
	v_cvt_pk_bf16_f32 v101, v106, v107
	v_exp_f32_e32 v112, v112
	v_exp_f32_e32 v113, v113
	v_exp_f32_e32 v114, v114
	v_exp_f32_e32 v115, v115
	v_add_f32_e32 v141, v141, v108
	v_add_f32_e32 v166, v166, v109
	v_add_f32_e32 v141, v141, v110
	v_add_f32_e32 v166, v166, v111
	v_cvt_pk_bf16_f32 v102, v108, v109
	v_cvt_pk_bf16_f32 v103, v110, v111
	v_exp_f32_e32 v116, v116
	v_exp_f32_e32 v117, v117
	v_exp_f32_e32 v118, v118
	v_exp_f32_e32 v119, v119
	v_add_f32_e32 v141, v141, v112
	v_add_f32_e32 v166, v166, v113
	v_add_f32_e32 v141, v141, v114
	v_add_f32_e32 v166, v166, v115
	v_cvt_pk_bf16_f32 v104, v112, v113
	v_cvt_pk_bf16_f32 v105, v114, v115
	v_exp_f32_e32 v120, v120
	s_waitcnt lgkmcnt(4)
	v_mfma_f32_32x32x16_bf16 v[16:31], v[176:179], v[76:79], v[16:31]
	v_mfma_f32_32x32x16_bf16 v[0:15], v[180:183], v[76:79], v[0:15]
	ds_read_b64_tr_b16 v[176:177], v158 offset:35840
	ds_read_b64_tr_b16 v[178:179], v158 offset:36352
	ds_read_b64_tr_b16 v[180:181], v158 offset:39936
	ds_read_b64_tr_b16 v[182:183], v158 offset:40448
	v_exp_f32_e32 v121, v121
	v_exp_f32_e32 v122, v122
	v_exp_f32_e32 v123, v123
	v_add_f32_e32 v141, v141, v116
	v_add_f32_e32 v166, v166, v117
	v_add_f32_e32 v141, v141, v118
	v_add_f32_e32 v166, v166, v119
	v_cvt_pk_bf16_f32 v106, v116, v117
	v_cvt_pk_bf16_f32 v107, v118, v119
	v_exp_f32_e32 v124, v124
	v_exp_f32_e32 v125, v125
	v_exp_f32_e32 v126, v126
	v_exp_f32_e32 v127, v127
	v_add_f32_e32 v141, v141, v120
	v_add_f32_e32 v166, v166, v121
	v_add_f32_e32 v141, v141, v122
	v_add_f32_e32 v166, v166, v123
	v_cvt_pk_bf16_f32 v108, v120, v121
	v_cvt_pk_bf16_f32 v109, v122, v123
	v_add_f32_e32 v141, v141, v124
	v_add_f32_e32 v166, v166, v125
	v_add_f32_e32 v141, v141, v126
	v_add_f32_e32 v166, v166, v127
	v_cvt_pk_bf16_f32 v110, v124, v125
	v_cvt_pk_bf16_f32 v111, v126, v127
	v_add_f32_e32 v141, v141, v166
	s_waitcnt lgkmcnt(4)
	v_mfma_f32_32x32x16_bf16 v[48:63], v[128:131], v[96:99], v[48:63]
	v_mfma_f32_32x32x16_bf16 v[32:47], v[142:145], v[96:99], v[32:47]
	ds_read_b64_tr_b16 v[128:129], v158 offset:36864
	ds_read_b64_tr_b16 v[130:131], v158 offset:37376
	ds_read_b64_tr_b16 v[142:143], v158 offset:40960
	ds_read_b64_tr_b16 v[144:145], v158 offset:41472
	s_waitcnt lgkmcnt(4)
	v_mfma_f32_32x32x16_bf16 v[48:63], v[176:179], v[100:103], v[48:63]
	v_mfma_f32_32x32x16_bf16 v[32:47], v[180:183], v[100:103], v[32:47]
	ds_read_b64_tr_b16 v[176:177], v158 offset:37888
	ds_read_b64_tr_b16 v[178:179], v158 offset:38400
	ds_read_b64_tr_b16 v[180:181], v158 offset:41984
	ds_read_b64_tr_b16 v[182:183], v158 offset:42496
	s_waitcnt lgkmcnt(4)
	v_mfma_f32_32x32x16_bf16 v[48:63], v[128:131], v[104:107], v[48:63]
	v_mfma_f32_32x32x16_bf16 v[32:47], v[142:145], v[104:107], v[32:47]
	s_waitcnt lgkmcnt(0)
	v_mfma_f32_32x32x16_bf16 v[48:63], v[176:179], v[108:111], v[48:63]
	v_mfma_f32_32x32x16_bf16 v[32:47], v[180:183], v[108:111], v[32:47]
	s_waitcnt lgkmcnt(0)
	s_barrier
	s_setprio 0
	s_nop 7
	s_nop 3
	s_branch .LBB0_75
